# LayerNorm GEMM epilogues (w_out, w_down): residual tile loads issued four at a time per 16-row block with counted waits instead of one load + full wait each
# speedup vs baseline: 1.0140x; 1.0140x over previous
.LBB0_812:
	s_lshr_b32 s1, s50, 3
	s_lshl_b32 s6, s50, 8
	v_mov_b32_e32 v0, v148
	s_mulk_i32 s1, 0x880
	s_and_b32 s6, s6, 0x700
	s_lshl_b32 s0, s65, 5
	s_barrier
	s_add_i32 s7, s1, s6
	s_lshl_b32 s1, s14, 8
	v_bfe_u32 v136, v0, 4, 2
	s_addk_i32 s7, 0x80
	v_and_or_b32 v0, v0, 15, s66
	s_or_b32 s0, s1, s0
	v_lshl_or_b32 v134, v136, 2, s0
	v_cmp_eq_u32_e32 vcc, 0, v136
	v_add_u32_e32 v136, s7, v0
	v_ashrrev_i32_e32 v137, 31, v136
	v_lshlrev_b64 v[138:139], 13, v[136:137]
	v_ashrrev_i32_e32 v135, 31, v134
	v_lshl_add_u64 v[138:139], s[28:29], 0, v[138:139]
	v_mov_b32_e32 v140, v148
	v_lshl_add_u64 v[146:147], v[134:135], 2, v[138:139]
	global_load_dwordx4 v[174:177], v[146:147], off
	global_load_dwordx4 v[178:181], v[146:147], off offset:64
	global_load_dwordx4 v[182:185], v[146:147], off offset:512
	global_load_dwordx4 v[186:189], v[146:147], off offset:576
	s_mov_b32 s0, 0x3fb504f3
	v_mov_b32_e32 v141, v148
	s_lshl_b32 s6, s65, 9
	s_waitcnt vmcnt(3)
	v_pk_fma_f32 v[128:129], v[176:177], s[0:1], v[128:129] op_sel_hi:[1,0,1]
	v_pk_fma_f32 v[126:127], v[174:175], s[0:1], v[126:127] op_sel_hi:[1,0,1]

	v_add_f32_e32 v152, v126, v127
	v_add_f32_e32 v154, v128, v129
	v_mul_f32_e32 v157, v126, v126
	v_mul_f32_e32 v159, v127, v127
	v_mul_f32_e32 v161, v128, v128
	v_mul_f32_e32 v163, v129, v129
	s_waitcnt vmcnt(2)
	v_pk_fma_f32 v[124:125], v[180:181], s[0:1], v[124:125] op_sel_hi:[1,0,1]
	v_pk_fma_f32 v[122:123], v[178:179], s[0:1], v[122:123] op_sel_hi:[1,0,1]
	v_mul_f32_e32 v142, v124, v124
	v_pk_fma_f32 v[164:165], v[124:125], v[124:125], v[142:143] op_sel_hi:[1,1,0]

	v_mul_f32_e32 v153, v122, v122
	v_mul_f32_e32 v155, v123, v123
	v_mov_b32_e32 v156, v122
	v_mov_b32_e32 v158, v123
	v_mov_b32_e32 v160, v124
	v_mov_b32_e32 v162, v125
	v_pk_add_f32 v[156:157], v[156:157], v[158:159]
	v_pk_add_f32 v[158:159], v[160:161], v[162:163]
	v_pk_add_f32 v[152:153], v[152:153], v[154:155]
	v_mov_b32_e32 v164, v1
	v_pk_add_f32 v[156:157], v[156:157], v[158:159]
	v_pk_add_f32 v[152:153], v[152:153], v[164:165]
	s_waitcnt vmcnt(1)
	v_pk_fma_f32 v[120:121], v[184:185], s[0:1], v[120:121] op_sel_hi:[1,0,1]
	v_pk_fma_f32 v[118:119], v[182:183], s[0:1], v[118:119] op_sel_hi:[1,0,1]

	v_mul_f32_e32 v167, v118, v118
	v_mul_f32_e32 v169, v119, v119
	v_mul_f32_e32 v171, v120, v120
	v_mul_f32_e32 v173, v121, v121
	v_mov_b32_e32 v166, v118
	v_mov_b32_e32 v168, v119
	v_mov_b32_e32 v170, v120
	v_mov_b32_e32 v172, v121
	v_pk_add_f32 v[152:153], v[156:157], v[152:153]
	v_pk_add_f32 v[154:155], v[166:167], v[168:169]
	v_pk_add_f32 v[156:157], v[170:171], v[172:173]
	v_lshlrev_b32_e32 v141, 2, v141
	v_pk_add_f32 v[154:155], v[154:155], v[156:157]
	v_bitop3_b32 v141, v141, 64, v232 bitop3:0x6c
	v_pk_add_f32 v[152:153], v[152:153], v[154:155]
	s_waitcnt vmcnt(0)
	v_pk_fma_f32 v[114:115], v[186:187], s[0:1], v[114:115] op_sel_hi:[1,0,1]
	v_mov_b32_e32 v142, v148
	v_pk_fma_f32 v[116:117], v[188:189], s[0:1], v[116:117] op_sel_hi:[1,0,1]
	v_lshlrev_b32_e32 v142, 2, v142
	v_mul_f32_e32 v143, v114, v114
	v_mul_f32_e32 v145, v115, v115
	v_mul_f32_e32 v147, v116, v116
	v_mul_f32_e32 v175, v117, v117
	v_bitop3_b32 v149, v142, 64, v232 bitop3:0x6c
	v_mov_b32_e32 v142, v114
	v_mov_b32_e32 v144, v115
	v_mov_b32_e32 v146, v116
	v_mov_b32_e32 v174, v117
	v_pk_add_f32 v[142:143], v[142:143], v[144:145]
	v_pk_add_f32 v[144:145], v[146:147], v[174:175]
	s_movk_i32 s0, 0x80
	v_pk_add_f32 v[142:143], v[142:143], v[144:145]
	s_nop 0
	v_pk_add_f32 v[142:143], v[152:153], v[142:143]
	ds_bpermute_b32 v144, v141, v142
	ds_bpermute_b32 v145, v149, v143
	v_mov_b32_e32 v141, v148
	s_waitcnt lgkmcnt(0)
	v_pk_add_f32 v[142:143], v[142:143], v[144:145]
	v_lshlrev_b32_e32 v141, 2, v141
	v_bitop3_b32 v141, v141, s0, v232 bitop3:0x6c
	ds_bpermute_b32 v144, v141, v142
	v_mov_b32_e32 v141, v148
	s_nop 0
	v_lshlrev_b32_e32 v141, 2, v141
	v_bitop3_b32 v141, v141, s0, v232 bitop3:0x6c
	ds_bpermute_b32 v145, v141, v143
	s_and_saveexec_b64 s[0:1], vcc
	v_readlane_b32 s40, v254, 48
	s_movk_i32 s41, 0x5000
	s_mov_b64 s[42:43], 0xac00
	s_mov_b64 s[44:45], 0x5600
	s_cbranch_execz .LBB0_814
	s_lshl_b32 s8, s6, 2
	s_add_i32 s8, s8, 0
	v_lshl_add_u32 v141, v0, 3, s8
	s_waitcnt lgkmcnt(0)
	v_pk_add_f32 v[142:143], v[142:143], v[144:145]
	ds_write_b64 v141, v[142:143]
.LBB0_814:
	s_or_b64 exec, exec, s[0:1]
	v_or_b32_e32 v149, 16, v0
	v_add_u32_e32 v142, s7, v149
	v_ashrrev_i32_e32 v143, 31, v142
	s_waitcnt lgkmcnt(0)
	v_lshlrev_b64 v[144:145], 13, v[142:143]
	v_lshl_add_u64 v[144:145], s[28:29], 0, v[144:145]
	v_lshl_add_u64 v[146:147], v[134:135], 2, v[144:145]
	global_load_dwordx4 v[182:185], v[146:147], off
	global_load_dwordx4 v[186:189], v[146:147], off offset:64
	global_load_dwordx4 v[190:193], v[146:147], off offset:512
	global_load_dwordx4 v[194:197], v[146:147], off offset:576
	s_mov_b32 s0, 0x3fb504f3
	v_mov_b32_e32 v141, v148
	s_waitcnt vmcnt(3)
	v_pk_fma_f32 v[112:113], v[184:185], s[0:1], v[112:113] op_sel_hi:[1,0,1]
	v_pk_fma_f32 v[110:111], v[182:183], s[0:1], v[110:111] op_sel_hi:[1,0,1]

	v_add_f32_e32 v156, v110, v111
	v_add_f32_e32 v158, v112, v113
	v_mul_f32_e32 v161, v110, v110
	v_mul_f32_e32 v163, v111, v111
	v_mul_f32_e32 v165, v112, v112
	v_mul_f32_e32 v167, v113, v113
	s_waitcnt vmcnt(2)
	v_pk_fma_f32 v[108:109], v[188:189], s[0:1], v[108:109] op_sel_hi:[1,0,1]
	v_pk_fma_f32 v[106:107], v[186:187], s[0:1], v[106:107] op_sel_hi:[1,0,1]
	v_mul_f32_e32 v152, v108, v108
	v_pk_fma_f32 v[168:169], v[108:109], v[108:109], v[152:153] op_sel_hi:[1,1,0]

	v_mul_f32_e32 v157, v106, v106
	v_mul_f32_e32 v159, v107, v107
	v_mov_b32_e32 v160, v106
	v_mov_b32_e32 v162, v107
	v_mov_b32_e32 v164, v108
	v_mov_b32_e32 v166, v109
	v_pk_add_f32 v[160:161], v[160:161], v[162:163]
	v_pk_add_f32 v[162:163], v[164:165], v[166:167]
	v_pk_add_f32 v[156:157], v[156:157], v[158:159]
	v_mov_b32_e32 v168, v1
	v_pk_add_f32 v[160:161], v[160:161], v[162:163]
	v_pk_add_f32 v[156:157], v[156:157], v[168:169]
	s_waitcnt vmcnt(1)
	v_pk_fma_f32 v[104:105], v[192:193], s[0:1], v[104:105] op_sel_hi:[1,0,1]
	v_pk_fma_f32 v[102:103], v[190:191], s[0:1], v[102:103] op_sel_hi:[1,0,1]

	v_mov_b32_e32 v146, v148
	v_mul_f32_e32 v171, v102, v102
	v_mul_f32_e32 v173, v103, v103
	v_mul_f32_e32 v175, v104, v104
	v_mul_f32_e32 v177, v105, v105
	v_lshlrev_b32_e32 v146, 2, v146
	v_mov_b32_e32 v170, v102
	v_mov_b32_e32 v172, v103
	v_mov_b32_e32 v174, v104
	v_mov_b32_e32 v176, v105
	v_bitop3_b32 v180, v146, 64, v232 bitop3:0x6c
	v_pk_add_f32 v[156:157], v[160:161], v[156:157]
	v_pk_add_f32 v[158:159], v[170:171], v[172:173]
	v_pk_add_f32 v[160:161], v[174:175], v[176:177]
	v_lshlrev_b32_e32 v141, 2, v141
	v_pk_add_f32 v[158:159], v[158:159], v[160:161]
	v_bitop3_b32 v141, v141, 64, v232 bitop3:0x6c
	v_pk_add_f32 v[156:157], v[156:157], v[158:159]
	s_waitcnt vmcnt(0)
	v_pk_fma_f32 v[100:101], v[196:197], s[0:1], v[100:101] op_sel_hi:[1,0,1]
	v_pk_fma_f32 v[98:99], v[194:195], s[0:1], v[98:99] op_sel_hi:[1,0,1]
	v_mul_f32_e32 v155, v100, v100
	v_mul_f32_e32 v147, v98, v98
	v_mul_f32_e32 v153, v99, v99
	v_mul_f32_e32 v179, v101, v101
	v_mov_b32_e32 v146, v98
	v_mov_b32_e32 v152, v99
	v_mov_b32_e32 v154, v100
	v_mov_b32_e32 v178, v101
	v_pk_add_f32 v[146:147], v[146:147], v[152:153]
	v_pk_add_f32 v[152:153], v[154:155], v[178:179]
	s_movk_i32 s0, 0x80
	v_pk_add_f32 v[146:147], v[146:147], v[152:153]
	s_nop 0
	v_pk_add_f32 v[146:147], v[156:157], v[146:147]
	ds_bpermute_b32 v152, v141, v146
	ds_bpermute_b32 v153, v180, v147
	v_mov_b32_e32 v141, v148
	s_waitcnt lgkmcnt(0)
	v_pk_add_f32 v[146:147], v[146:147], v[152:153]
	v_lshlrev_b32_e32 v141, 2, v141
	v_bitop3_b32 v141, v141, s0, v232 bitop3:0x6c
	ds_bpermute_b32 v156, v141, v146
	v_mov_b32_e32 v141, v148
	s_nop 0
	v_lshlrev_b32_e32 v141, 2, v141
	v_bitop3_b32 v141, v141, s0, v232 bitop3:0x6c
	ds_bpermute_b32 v157, v141, v147
	s_and_saveexec_b64 s[0:1], vcc
	s_cbranch_execz .LBB0_816
	s_lshl_b32 s8, s6, 2
	s_add_i32 s8, s8, 0
	v_lshl_add_u32 v141, v149, 3, s8
	s_waitcnt lgkmcnt(0)
	v_pk_add_f32 v[146:147], v[146:147], v[156:157]
	ds_write_b64 v141, v[146:147]
.LBB0_816:
	s_or_b64 exec, exec, s[0:1]
	v_or_b32_e32 v215, 32, v0
	v_add_u32_e32 v146, s7, v215
	v_ashrrev_i32_e32 v147, 31, v146
	v_lshlrev_b64 v[152:153], 13, v[146:147]
	s_waitcnt lgkmcnt(0)
	v_lshl_add_u64 v[156:157], s[28:29], 0, v[152:153]
	v_lshl_add_u64 v[158:159], v[134:135], 2, v[156:157]
	global_load_dwordx4 v[184:187], v[158:159], off
	global_load_dwordx4 v[188:191], v[158:159], off offset:64
	global_load_dwordx4 v[192:195], v[158:159], off offset:512
	global_load_dwordx4 v[196:199], v[158:159], off offset:576
	s_mov_b32 s0, 0x3fb504f3
	s_waitcnt vmcnt(3)
	v_pk_fma_f32 v[96:97], v[186:187], s[0:1], v[96:97] op_sel_hi:[1,0,1]
	v_pk_fma_f32 v[94:95], v[184:185], s[0:1], v[94:95] op_sel_hi:[1,0,1]

	v_add_f32_e32 v162, v94, v95
	v_add_f32_e32 v164, v96, v97
	v_mul_f32_e32 v167, v94, v94
	v_mul_f32_e32 v169, v95, v95
	v_mul_f32_e32 v171, v96, v96
	v_mul_f32_e32 v173, v97, v97
	s_waitcnt vmcnt(2)
	v_pk_fma_f32 v[92:93], v[190:191], s[0:1], v[92:93] op_sel_hi:[1,0,1]
	v_pk_fma_f32 v[90:91], v[188:189], s[0:1], v[90:91] op_sel_hi:[1,0,1]
	v_mul_f32_e32 v152, v92, v92
	v_pk_fma_f32 v[174:175], v[92:93], v[92:93], v[152:153] op_sel_hi:[1,1,0]

	v_mul_f32_e32 v163, v90, v90
	v_mul_f32_e32 v165, v91, v91
	v_mov_b32_e32 v166, v90
	v_mov_b32_e32 v168, v91
	v_mov_b32_e32 v170, v92
	v_mov_b32_e32 v172, v93
	v_pk_add_f32 v[166:167], v[166:167], v[168:169]
	v_pk_add_f32 v[168:169], v[170:171], v[172:173]
	v_pk_add_f32 v[162:163], v[162:163], v[164:165]
	v_mov_b32_e32 v174, v1
	v_pk_add_f32 v[166:167], v[166:167], v[168:169]
	v_pk_add_f32 v[162:163], v[162:163], v[174:175]
	s_waitcnt vmcnt(1)
	v_pk_fma_f32 v[88:89], v[194:195], s[0:1], v[88:89] op_sel_hi:[1,0,1]
	v_pk_fma_f32 v[86:87], v[192:193], s[0:1], v[86:87] op_sel_hi:[1,0,1]

	v_mul_f32_e32 v177, v86, v86
	v_mul_f32_e32 v179, v87, v87
	v_mul_f32_e32 v181, v88, v88
	v_mul_f32_e32 v183, v89, v89
	v_mov_b32_e32 v176, v86
	v_mov_b32_e32 v178, v87
	v_mov_b32_e32 v180, v88
	v_mov_b32_e32 v182, v89
	v_pk_add_f32 v[162:163], v[166:167], v[162:163]
	v_pk_add_f32 v[164:165], v[176:177], v[178:179]
	v_pk_add_f32 v[166:167], v[180:181], v[182:183]
	s_waitcnt vmcnt(0)
	v_pk_fma_f32 v[160:161], v[196:197], s[0:1], v[82:83] op_sel_hi:[1,0,1]
	v_mov_b32_e32 v82, v148
	v_pk_fma_f32 v[158:159], v[198:199], s[0:1], v[84:85] op_sel_hi:[1,0,1]
	v_lshlrev_b32_e32 v82, 2, v82
	v_bitop3_b32 v141, v82, 64, v232 bitop3:0x6c
	v_mov_b32_e32 v82, v148
	v_mul_f32_e32 v83, v160, v160
	v_lshlrev_b32_e32 v82, 2, v82
	v_mul_f32_e32 v85, v161, v161
	v_mul_f32_e32 v153, v158, v158
	v_mul_f32_e32 v155, v159, v159
	v_bitop3_b32 v184, v82, 64, v232 bitop3:0x6c
	v_mov_b32_e32 v82, v160
	v_mov_b32_e32 v84, v161
	v_mov_b32_e32 v152, v158
	v_mov_b32_e32 v154, v159
	v_pk_add_f32 v[164:165], v[164:165], v[166:167]
	v_pk_add_f32 v[82:83], v[82:83], v[84:85]
	v_pk_add_f32 v[84:85], v[152:153], v[154:155]
	v_pk_add_f32 v[162:163], v[162:163], v[164:165]
	v_pk_add_f32 v[82:83], v[82:83], v[84:85]
	s_movk_i32 s0, 0x80
	v_pk_add_f32 v[82:83], v[162:163], v[82:83]
	ds_bpermute_b32 v84, v141, v82
	ds_bpermute_b32 v85, v184, v83
	s_waitcnt lgkmcnt(0)
	v_pk_add_f32 v[82:83], v[82:83], v[84:85]
	v_mov_b32_e32 v84, v148
	v_mov_b32_e32 v85, v148
	s_nop 0
	v_lshlrev_b32_e32 v84, 2, v84
	v_lshlrev_b32_e32 v85, 2, v85
	v_bitop3_b32 v84, v84, s0, v232 bitop3:0x6c
	v_bitop3_b32 v85, v85, s0, v232 bitop3:0x6c
	ds_bpermute_b32 v84, v84, v82
	ds_bpermute_b32 v85, v85, v83
	s_and_saveexec_b64 s[0:1], vcc
	s_cbranch_execz .LBB0_818
	s_lshl_b32 s8, s6, 2
	s_add_i32 s8, s8, 0
	v_lshl_add_u32 v141, v215, 3, s8
	s_waitcnt lgkmcnt(0)
	v_pk_add_f32 v[82:83], v[82:83], v[84:85]
	ds_write_b64 v141, v[82:83]
.LBB0_818:
	s_or_b64 exec, exec, s[0:1]
	v_or_b32_e32 v216, 48, v0
	v_add_u32_e32 v82, s7, v216
	v_ashrrev_i32_e32 v83, 31, v82
	s_waitcnt lgkmcnt(0)
	v_lshlrev_b64 v[84:85], 13, v[82:83]
	v_lshl_add_u64 v[84:85], s[28:29], 0, v[84:85]
	v_lshl_add_u64 v[162:163], v[134:135], 2, v[84:85]
	global_load_dwordx4 v[186:189], v[162:163], off
	global_load_dwordx4 v[190:193], v[162:163], off offset:64
	global_load_dwordx4 v[194:197], v[162:163], off offset:512
	global_load_dwordx4 v[198:201], v[162:163], off offset:576
	s_mov_b32 s0, 0x3fb504f3
	v_mov_b32_e32 v141, v148
	s_waitcnt vmcnt(3)
	v_pk_fma_f32 v[80:81], v[188:189], s[0:1], v[80:81] op_sel_hi:[1,0,1]
	v_pk_fma_f32 v[78:79], v[186:187], s[0:1], v[78:79] op_sel_hi:[1,0,1]

	v_add_f32_e32 v164, v78, v79
	v_add_f32_e32 v166, v80, v81
	v_mul_f32_e32 v169, v78, v78
	v_mul_f32_e32 v171, v79, v79
	v_mul_f32_e32 v173, v80, v80
	v_mul_f32_e32 v175, v81, v81
	s_waitcnt vmcnt(2)
	v_pk_fma_f32 v[76:77], v[192:193], s[0:1], v[76:77] op_sel_hi:[1,0,1]
	v_pk_fma_f32 v[74:75], v[190:191], s[0:1], v[74:75] op_sel_hi:[1,0,1]
	v_mul_f32_e32 v152, v76, v76
	v_pk_fma_f32 v[176:177], v[76:77], v[76:77], v[152:153] op_sel_hi:[1,1,0]

	v_mul_f32_e32 v165, v74, v74
	v_mul_f32_e32 v167, v75, v75
	v_mov_b32_e32 v168, v74
	v_mov_b32_e32 v170, v75
	v_mov_b32_e32 v172, v76
	v_mov_b32_e32 v174, v77
	v_pk_add_f32 v[168:169], v[168:169], v[170:171]
	v_pk_add_f32 v[170:171], v[172:173], v[174:175]
	v_pk_add_f32 v[164:165], v[164:165], v[166:167]
	v_mov_b32_e32 v176, v1
	v_pk_add_f32 v[168:169], v[168:169], v[170:171]
	v_pk_add_f32 v[164:165], v[164:165], v[176:177]
	s_waitcnt vmcnt(1)
	v_pk_fma_f32 v[72:73], v[196:197], s[0:1], v[72:73] op_sel_hi:[1,0,1]
	v_pk_fma_f32 v[70:71], v[194:195], s[0:1], v[70:71] op_sel_hi:[1,0,1]

	v_mul_f32_e32 v179, v70, v70
	v_mul_f32_e32 v181, v71, v71
	v_mul_f32_e32 v183, v72, v72
	v_mul_f32_e32 v185, v73, v73
	v_mov_b32_e32 v178, v70
	v_mov_b32_e32 v180, v71
	v_mov_b32_e32 v182, v72
	v_mov_b32_e32 v184, v73
	v_pk_add_f32 v[164:165], v[168:169], v[164:165]
	v_pk_add_f32 v[166:167], v[178:179], v[180:181]
	v_pk_add_f32 v[168:169], v[182:183], v[184:185]
	v_lshlrev_b32_e32 v141, 2, v141
	v_pk_add_f32 v[166:167], v[166:167], v[168:169]
	v_bitop3_b32 v141, v141, 64, v232 bitop3:0x6c
	v_pk_add_f32 v[164:165], v[164:165], v[166:167]
	s_waitcnt vmcnt(0)
	v_pk_fma_f32 v[66:67], v[198:199], s[0:1], v[66:67] op_sel_hi:[1,0,1]
	v_mov_b32_e32 v152, v148
	v_pk_fma_f32 v[68:69], v[200:201], s[0:1], v[68:69] op_sel_hi:[1,0,1]
	v_lshlrev_b32_e32 v152, 2, v152
	v_mul_f32_e32 v153, v66, v66
	v_mul_f32_e32 v155, v67, v67
	v_mul_f32_e32 v163, v68, v68
	v_mul_f32_e32 v187, v69, v69
	v_bitop3_b32 v188, v152, 64, v232 bitop3:0x6c
	v_mov_b32_e32 v152, v66
	v_mov_b32_e32 v154, v67
	v_mov_b32_e32 v162, v68
	v_mov_b32_e32 v186, v69
	v_pk_add_f32 v[152:153], v[152:153], v[154:155]
	v_pk_add_f32 v[154:155], v[162:163], v[186:187]
	s_movk_i32 s0, 0x80
	v_pk_add_f32 v[152:153], v[152:153], v[154:155]
	s_nop 0
	v_pk_add_f32 v[152:153], v[164:165], v[152:153]
	ds_bpermute_b32 v154, v141, v152
	ds_bpermute_b32 v155, v188, v153
	v_mov_b32_e32 v141, v148
	s_waitcnt lgkmcnt(0)
	v_pk_add_f32 v[162:163], v[152:153], v[154:155]
	v_lshlrev_b32_e32 v141, 2, v141
	v_bitop3_b32 v141, v141, s0, v232 bitop3:0x6c
	ds_bpermute_b32 v164, v141, v162
	v_mov_b32_e32 v141, v148
	s_nop 0
	v_lshlrev_b32_e32 v141, 2, v141
	v_bitop3_b32 v141, v141, s0, v232 bitop3:0x6c
	ds_bpermute_b32 v165, v141, v163
	s_and_saveexec_b64 s[0:1], vcc
	s_cbranch_execz .LBB0_820
	s_lshl_b32 s8, s6, 2
	s_add_i32 s8, s8, 0
	v_lshl_add_u32 v141, v216, 3, s8
	s_waitcnt lgkmcnt(0)
	v_pk_add_f32 v[152:153], v[162:163], v[164:165]
	ds_write_b64 v141, v[152:153]
.LBB0_820:
	s_or_b64 exec, exec, s[0:1]
	v_add_u32_e32 v217, 0x80, v0
	v_add_u32_e32 v162, s7, v217
	v_ashrrev_i32_e32 v163, 31, v162
	v_lshlrev_b64 v[152:153], 13, v[162:163]
	s_waitcnt lgkmcnt(0)
	v_lshl_add_u64 v[164:165], s[28:29], 0, v[152:153]
	v_lshl_add_u64 v[166:167], v[134:135], 2, v[164:165]
	global_load_dwordx4 v[190:193], v[166:167], off
	global_load_dwordx4 v[194:197], v[166:167], off offset:64
	global_load_dwordx4 v[198:201], v[166:167], off offset:512
	global_load_dwordx4 v[202:205], v[166:167], off offset:576
	s_mov_b32 s0, 0x3fb504f3
	v_mov_b32_e32 v141, v148
	s_waitcnt vmcnt(3)
	v_pk_fma_f32 v[64:65], v[192:193], s[0:1], v[64:65] op_sel_hi:[1,0,1]
	v_pk_fma_f32 v[62:63], v[190:191], s[0:1], v[62:63] op_sel_hi:[1,0,1]

	v_add_f32_e32 v168, v62, v63
	v_add_f32_e32 v170, v64, v65
	v_mul_f32_e32 v173, v62, v62
	v_mul_f32_e32 v175, v63, v63
	v_mul_f32_e32 v177, v64, v64
	v_mul_f32_e32 v179, v65, v65
	s_waitcnt vmcnt(2)
	v_pk_fma_f32 v[60:61], v[196:197], s[0:1], v[60:61] op_sel_hi:[1,0,1]
	v_pk_fma_f32 v[58:59], v[194:195], s[0:1], v[58:59] op_sel_hi:[1,0,1]
	v_mul_f32_e32 v152, v60, v60
	v_pk_fma_f32 v[180:181], v[60:61], v[60:61], v[152:153] op_sel_hi:[1,1,0]

	v_mul_f32_e32 v169, v58, v58
	v_mul_f32_e32 v171, v59, v59
	v_mov_b32_e32 v172, v58
	v_mov_b32_e32 v174, v59
	v_mov_b32_e32 v176, v60
	v_mov_b32_e32 v178, v61
	v_pk_add_f32 v[172:173], v[172:173], v[174:175]
	v_pk_add_f32 v[174:175], v[176:177], v[178:179]
	v_pk_add_f32 v[168:169], v[168:169], v[170:171]
	v_mov_b32_e32 v180, v1
	v_pk_add_f32 v[172:173], v[172:173], v[174:175]
	v_pk_add_f32 v[168:169], v[168:169], v[180:181]
	s_waitcnt vmcnt(1)
	v_pk_fma_f32 v[56:57], v[200:201], s[0:1], v[56:57] op_sel_hi:[1,0,1]
	v_pk_fma_f32 v[54:55], v[198:199], s[0:1], v[54:55] op_sel_hi:[1,0,1]

	v_mul_f32_e32 v183, v54, v54
	v_mul_f32_e32 v185, v55, v55
	v_mul_f32_e32 v187, v56, v56
	v_mul_f32_e32 v189, v57, v57
	v_mov_b32_e32 v182, v54
	v_mov_b32_e32 v184, v55
	v_mov_b32_e32 v186, v56
	v_mov_b32_e32 v188, v57
	v_pk_add_f32 v[168:169], v[172:173], v[168:169]
	v_pk_add_f32 v[170:171], v[182:183], v[184:185]
	v_pk_add_f32 v[172:173], v[186:187], v[188:189]
	v_lshlrev_b32_e32 v141, 2, v141
	v_pk_add_f32 v[170:171], v[170:171], v[172:173]
	v_bitop3_b32 v141, v141, 64, v232 bitop3:0x6c
	v_pk_add_f32 v[168:169], v[168:169], v[170:171]
	s_waitcnt vmcnt(0)
	v_pk_fma_f32 v[50:51], v[202:203], s[0:1], v[50:51] op_sel_hi:[1,0,1]
	v_mov_b32_e32 v152, v148
	v_pk_fma_f32 v[52:53], v[204:205], s[0:1], v[52:53] op_sel_hi:[1,0,1]
	v_lshlrev_b32_e32 v152, 2, v152
	v_mul_f32_e32 v153, v50, v50
	v_mul_f32_e32 v155, v51, v51
	v_mul_f32_e32 v167, v52, v52
	v_mul_f32_e32 v191, v53, v53
	v_bitop3_b32 v192, v152, 64, v232 bitop3:0x6c
	v_mov_b32_e32 v152, v50
	v_mov_b32_e32 v154, v51
	v_mov_b32_e32 v166, v52
	v_mov_b32_e32 v190, v53
	v_pk_add_f32 v[152:153], v[152:153], v[154:155]
	v_pk_add_f32 v[154:155], v[166:167], v[190:191]
	s_movk_i32 s0, 0x80
	v_pk_add_f32 v[152:153], v[152:153], v[154:155]
	s_nop 0
	v_pk_add_f32 v[152:153], v[168:169], v[152:153]
	ds_bpermute_b32 v154, v141, v152
	ds_bpermute_b32 v155, v192, v153
	v_mov_b32_e32 v141, v148
	s_waitcnt lgkmcnt(0)
	v_pk_add_f32 v[166:167], v[152:153], v[154:155]
	v_lshlrev_b32_e32 v141, 2, v141
	v_bitop3_b32 v141, v141, s0, v232 bitop3:0x6c
	ds_bpermute_b32 v168, v141, v166
	v_mov_b32_e32 v141, v148
	s_nop 0
	v_lshlrev_b32_e32 v141, 2, v141
	v_bitop3_b32 v141, v141, s0, v232 bitop3:0x6c
	ds_bpermute_b32 v169, v141, v167
	s_and_saveexec_b64 s[0:1], vcc
	s_cbranch_execz .LBB0_822
	s_lshl_b32 s8, s6, 2
	s_add_i32 s8, s8, 0
	v_lshl_add_u32 v141, v217, 3, s8
	s_waitcnt lgkmcnt(0)
	v_pk_add_f32 v[152:153], v[166:167], v[168:169]
	ds_write_b64 v141, v[152:153]
.LBB0_822:
	s_or_b64 exec, exec, s[0:1]
	v_add_u32_e32 v218, 0x90, v0
	v_add_u32_e32 v166, s7, v218
	v_ashrrev_i32_e32 v167, 31, v166
	v_lshlrev_b64 v[152:153], 13, v[166:167]
	s_waitcnt lgkmcnt(0)
	v_lshl_add_u64 v[168:169], s[28:29], 0, v[152:153]
	v_lshl_add_u64 v[170:171], v[134:135], 2, v[168:169]
	global_load_dwordx4 v[194:197], v[170:171], off
	global_load_dwordx4 v[198:201], v[170:171], off offset:64
	global_load_dwordx4 v[202:205], v[170:171], off offset:512
	global_load_dwordx4 v[206:209], v[170:171], off offset:576
	s_mov_b32 s0, 0x3fb504f3
	v_mov_b32_e32 v141, v148
	s_waitcnt vmcnt(3)
	v_pk_fma_f32 v[48:49], v[196:197], s[0:1], v[48:49] op_sel_hi:[1,0,1]
	v_pk_fma_f32 v[46:47], v[194:195], s[0:1], v[46:47] op_sel_hi:[1,0,1]

	v_add_f32_e32 v172, v46, v47
	v_add_f32_e32 v174, v48, v49
	v_mul_f32_e32 v177, v46, v46
	v_mul_f32_e32 v179, v47, v47
	v_mul_f32_e32 v181, v48, v48
	v_mul_f32_e32 v183, v49, v49
	s_waitcnt vmcnt(2)
	v_pk_fma_f32 v[44:45], v[200:201], s[0:1], v[44:45] op_sel_hi:[1,0,1]
	v_pk_fma_f32 v[42:43], v[198:199], s[0:1], v[42:43] op_sel_hi:[1,0,1]
	v_mul_f32_e32 v152, v44, v44
	v_pk_fma_f32 v[184:185], v[44:45], v[44:45], v[152:153] op_sel_hi:[1,1,0]

	v_mul_f32_e32 v173, v42, v42
	v_mul_f32_e32 v175, v43, v43
	v_mov_b32_e32 v176, v42
	v_mov_b32_e32 v178, v43
	v_mov_b32_e32 v180, v44
	v_mov_b32_e32 v182, v45
	v_pk_add_f32 v[176:177], v[176:177], v[178:179]
	v_pk_add_f32 v[178:179], v[180:181], v[182:183]
	v_pk_add_f32 v[172:173], v[172:173], v[174:175]
	v_mov_b32_e32 v184, v1
	v_pk_add_f32 v[176:177], v[176:177], v[178:179]
	v_pk_add_f32 v[172:173], v[172:173], v[184:185]
	s_waitcnt vmcnt(1)
	v_pk_fma_f32 v[40:41], v[204:205], s[0:1], v[40:41] op_sel_hi:[1,0,1]
	v_pk_fma_f32 v[38:39], v[202:203], s[0:1], v[38:39] op_sel_hi:[1,0,1]

	v_mul_f32_e32 v187, v38, v38
	v_mul_f32_e32 v189, v39, v39
	v_mul_f32_e32 v191, v40, v40
	v_mul_f32_e32 v193, v41, v41
	v_mov_b32_e32 v186, v38
	v_mov_b32_e32 v188, v39
	v_mov_b32_e32 v190, v40
	v_mov_b32_e32 v192, v41
	v_pk_add_f32 v[172:173], v[176:177], v[172:173]
	v_pk_add_f32 v[174:175], v[186:187], v[188:189]
	v_pk_add_f32 v[176:177], v[190:191], v[192:193]
	v_lshlrev_b32_e32 v141, 2, v141
	v_pk_add_f32 v[174:175], v[174:175], v[176:177]
	v_bitop3_b32 v141, v141, 64, v232 bitop3:0x6c
	v_pk_add_f32 v[172:173], v[172:173], v[174:175]
	s_waitcnt vmcnt(0)
	v_pk_fma_f32 v[34:35], v[206:207], s[0:1], v[34:35] op_sel_hi:[1,0,1]
	v_mov_b32_e32 v152, v148
	v_pk_fma_f32 v[36:37], v[208:209], s[0:1], v[36:37] op_sel_hi:[1,0,1]
	v_lshlrev_b32_e32 v152, 2, v152
	v_mul_f32_e32 v153, v34, v34
	v_mul_f32_e32 v155, v35, v35
	v_mul_f32_e32 v171, v36, v36
	v_mul_f32_e32 v195, v37, v37
	v_bitop3_b32 v196, v152, 64, v232 bitop3:0x6c
	v_mov_b32_e32 v152, v34
	v_mov_b32_e32 v154, v35
	v_mov_b32_e32 v170, v36
	v_mov_b32_e32 v194, v37
	v_pk_add_f32 v[152:153], v[152:153], v[154:155]
	v_pk_add_f32 v[154:155], v[170:171], v[194:195]
	s_movk_i32 s0, 0x80
	v_pk_add_f32 v[152:153], v[152:153], v[154:155]
	s_nop 0
	v_pk_add_f32 v[152:153], v[172:173], v[152:153]
	ds_bpermute_b32 v154, v141, v152
	ds_bpermute_b32 v155, v196, v153
	v_mov_b32_e32 v141, v148
	s_waitcnt lgkmcnt(0)
	v_pk_add_f32 v[170:171], v[152:153], v[154:155]
	v_lshlrev_b32_e32 v141, 2, v141
	v_bitop3_b32 v141, v141, s0, v232 bitop3:0x6c
	ds_bpermute_b32 v172, v141, v170
	v_mov_b32_e32 v141, v148
	s_nop 0
	v_lshlrev_b32_e32 v141, 2, v141
	v_bitop3_b32 v141, v141, s0, v232 bitop3:0x6c
	ds_bpermute_b32 v173, v141, v171
	s_and_saveexec_b64 s[0:1], vcc
	s_cbranch_execz .LBB0_824
	s_lshl_b32 s8, s6, 2
	s_add_i32 s8, s8, 0
	v_lshl_add_u32 v141, v218, 3, s8
	s_waitcnt lgkmcnt(0)
	v_pk_add_f32 v[152:153], v[170:171], v[172:173]
	ds_write_b64 v141, v[152:153]
.LBB0_824:
	s_or_b64 exec, exec, s[0:1]
	v_add_u32_e32 v219, 0xa0, v0
	v_add_u32_e32 v182, s7, v219
	v_ashrrev_i32_e32 v183, 31, v182
	v_lshlrev_b64 v[152:153], 13, v[182:183]
	v_lshl_add_u64 v[188:189], s[28:29], 0, v[152:153]
	v_lshl_add_u64 v[170:171], v[134:135], 2, v[188:189]
	global_load_dwordx4 v[184:187], v[170:171], off
	global_load_dwordx4 v[194:197], v[170:171], off offset:64
	global_load_dwordx4 v[220:223], v[170:171], off offset:512
	global_load_dwordx4 v[224:227], v[170:171], off offset:576
	s_mov_b32 s0, 0x3fb504f3
	s_waitcnt vmcnt(3)
	v_pk_fma_f32 v[192:193], v[186:187], s[0:1], v[32:33] op_sel_hi:[1,0,1]
	v_pk_fma_f32 v[190:191], v[184:185], s[0:1], v[30:31] op_sel_hi:[1,0,1]

	v_add_f32_e32 v152, v190, v191
	v_add_f32_e32 v154, v192, v193
	s_waitcnt lgkmcnt(0)
	v_mul_f32_e32 v173, v190, v190
	v_mul_f32_e32 v175, v191, v191
	v_mul_f32_e32 v177, v192, v192
	v_mul_f32_e32 v179, v193, v193
	s_waitcnt vmcnt(2)
	v_pk_fma_f32 v[200:201], v[196:197], s[0:1], v[28:29] op_sel_hi:[1,0,1]
	v_pk_fma_f32 v[198:199], v[194:195], s[0:1], v[26:27] op_sel_hi:[1,0,1]
	v_mul_f32_e32 v26, v200, v200
	v_pk_fma_f32 v[30:31], v[200:201], v[200:201], v[26:27] op_sel_hi:[1,1,0]

	v_mul_f32_e32 v153, v198, v198
	v_mul_f32_e32 v155, v199, v199
	v_mov_b32_e32 v172, v198
	v_mov_b32_e32 v174, v199
	v_mov_b32_e32 v176, v200
	v_mov_b32_e32 v178, v201
	v_pk_add_f32 v[152:153], v[152:153], v[154:155]
	v_mov_b32_e32 v30, v1
	v_pk_add_f32 v[30:31], v[152:153], v[30:31]
	s_waitcnt vmcnt(1)
	v_pk_fma_f32 v[204:205], v[222:223], s[0:1], v[24:25] op_sel_hi:[1,0,1]
	v_pk_fma_f32 v[202:203], v[220:221], s[0:1], v[22:23] op_sel_hi:[1,0,1]

	v_mul_f32_e32 v27, v202, v202
	v_mul_f32_e32 v29, v203, v203
	v_mul_f32_e32 v33, v204, v204
	v_mul_f32_e32 v181, v205, v205
	v_pk_add_f32 v[170:171], v[172:173], v[174:175]
	v_pk_add_f32 v[172:173], v[176:177], v[178:179]
	v_mov_b32_e32 v26, v202
	v_mov_b32_e32 v28, v203
	v_mov_b32_e32 v32, v204
	v_mov_b32_e32 v180, v205
	v_pk_add_f32 v[170:171], v[170:171], v[172:173]
	v_pk_add_f32 v[26:27], v[26:27], v[28:29]
	v_pk_add_f32 v[28:29], v[32:33], v[180:181]
	v_pk_add_f32 v[30:31], v[170:171], v[30:31]
	v_pk_add_f32 v[26:27], v[26:27], v[28:29]
	s_waitcnt vmcnt(0)
	v_pk_fma_f32 v[208:209], v[224:225], s[0:1], v[18:19] op_sel_hi:[1,0,1]
	v_mov_b32_e32 v18, v148
	v_pk_fma_f32 v[206:207], v[226:227], s[0:1], v[20:21] op_sel_hi:[1,0,1]
	v_lshlrev_b32_e32 v18, 2, v18
	v_bitop3_b32 v141, v18, 64, v232 bitop3:0x6c
	v_mov_b32_e32 v18, v148
	v_mul_f32_e32 v19, v208, v208
	v_lshlrev_b32_e32 v18, 2, v18
	v_mul_f32_e32 v21, v209, v209
	v_mul_f32_e32 v23, v206, v206
	v_mul_f32_e32 v25, v207, v207
	v_bitop3_b32 v184, v18, 64, v232 bitop3:0x6c
	v_mov_b32_e32 v18, v208
	v_mov_b32_e32 v20, v209
	v_mov_b32_e32 v22, v206
	v_mov_b32_e32 v24, v207
	v_pk_add_f32 v[18:19], v[18:19], v[20:21]
	v_pk_add_f32 v[20:21], v[22:23], v[24:25]
	v_pk_add_f32 v[26:27], v[30:31], v[26:27]
	v_pk_add_f32 v[18:19], v[18:19], v[20:21]
	s_movk_i32 s0, 0x80
	v_pk_add_f32 v[18:19], v[26:27], v[18:19]
	ds_bpermute_b32 v20, v141, v18
	ds_bpermute_b32 v21, v184, v19
	s_waitcnt lgkmcnt(0)
	v_pk_add_f32 v[18:19], v[18:19], v[20:21]
	v_mov_b32_e32 v20, v148
	v_mov_b32_e32 v21, v148
	s_nop 0
	v_lshlrev_b32_e32 v20, 2, v20
	v_lshlrev_b32_e32 v21, 2, v21
	v_bitop3_b32 v20, v20, s0, v232 bitop3:0x6c
	v_bitop3_b32 v21, v21, s0, v232 bitop3:0x6c
	ds_bpermute_b32 v20, v20, v18
	ds_bpermute_b32 v21, v21, v19
	s_and_saveexec_b64 s[0:1], vcc
	s_cbranch_execz .LBB0_826
	s_lshl_b32 s8, s6, 2
	s_add_i32 s8, s8, 0
	v_lshl_add_u32 v22, v219, 3, s8
	s_waitcnt lgkmcnt(0)
	v_pk_add_f32 v[18:19], v[18:19], v[20:21]
	ds_write_b64 v22, v[18:19]

.LBB0_1089:
	s_lshr_b32 s1, s50, 3
	s_lshl_b32 s6, s50, 8
	v_mov_b32_e32 v0, v148
	s_mulk_i32 s1, 0x880
	s_and_b32 s6, s6, 0x700
	s_lshl_b32 s0, s61, 5
	s_barrier
	s_add_i32 s7, s1, s6
	s_lshl_b32 s1, s14, 8
	v_bfe_u32 v138, v0, 4, 2
	s_addk_i32 s7, 0x80
	v_and_or_b32 v0, v0, 15, s64
	s_or_b32 s0, s1, s0
	v_lshl_or_b32 v136, v138, 2, s0
	v_cmp_eq_u32_e32 vcc, 0, v138
	v_add_u32_e32 v138, s7, v0
	v_ashrrev_i32_e32 v139, 31, v138
	v_lshlrev_b64 v[142:143], 13, v[138:139]
	v_ashrrev_i32_e32 v137, 31, v136
	v_lshl_add_u64 v[142:143], s[28:29], 0, v[142:143]
	v_mov_b32_e32 v140, v148
	v_lshl_add_u64 v[146:147], v[136:137], 2, v[142:143]
	global_load_dwordx4 v[174:177], v[146:147], off
	global_load_dwordx4 v[178:181], v[146:147], off offset:64
	global_load_dwordx4 v[182:185], v[146:147], off offset:512
	global_load_dwordx4 v[186:189], v[146:147], off offset:576
	s_mov_b32 s0, 0x3fb504f3
	v_mov_b32_e32 v141, v148
	s_lshl_b32 s6, s61, 9
	s_waitcnt vmcnt(3)
	v_pk_fma_f32 v[128:129], v[176:177], s[0:1], v[128:129] op_sel_hi:[1,0,1]
	v_pk_fma_f32 v[126:127], v[174:175], s[0:1], v[126:127] op_sel_hi:[1,0,1]

	v_add_f32_e32 v152, v126, v127
	v_add_f32_e32 v154, v128, v129
	v_mul_f32_e32 v157, v126, v126
	v_mul_f32_e32 v159, v127, v127
	v_mul_f32_e32 v161, v128, v128
	v_mul_f32_e32 v163, v129, v129
	s_waitcnt vmcnt(2)
	v_pk_fma_f32 v[124:125], v[180:181], s[0:1], v[124:125] op_sel_hi:[1,0,1]
	v_pk_fma_f32 v[122:123], v[178:179], s[0:1], v[122:123] op_sel_hi:[1,0,1]
	v_mul_f32_e32 v142, v124, v124
	v_pk_fma_f32 v[164:165], v[124:125], v[124:125], v[142:143] op_sel_hi:[1,1,0]

	v_mul_f32_e32 v153, v122, v122
	v_mul_f32_e32 v155, v123, v123
	v_mov_b32_e32 v156, v122
	v_mov_b32_e32 v158, v123
	v_mov_b32_e32 v160, v124
	v_mov_b32_e32 v162, v125
	v_pk_add_f32 v[156:157], v[156:157], v[158:159]
	v_pk_add_f32 v[158:159], v[160:161], v[162:163]
	v_pk_add_f32 v[152:153], v[152:153], v[154:155]
	v_mov_b32_e32 v164, v1
	v_pk_add_f32 v[156:157], v[156:157], v[158:159]
	v_pk_add_f32 v[152:153], v[152:153], v[164:165]
	s_waitcnt vmcnt(1)
	v_pk_fma_f32 v[120:121], v[184:185], s[0:1], v[120:121] op_sel_hi:[1,0,1]
	v_pk_fma_f32 v[118:119], v[182:183], s[0:1], v[118:119] op_sel_hi:[1,0,1]

	v_mul_f32_e32 v167, v118, v118
	v_mul_f32_e32 v169, v119, v119
	v_mul_f32_e32 v171, v120, v120
	v_mul_f32_e32 v173, v121, v121
	v_mov_b32_e32 v166, v118
	v_mov_b32_e32 v168, v119
	v_mov_b32_e32 v170, v120
	v_mov_b32_e32 v172, v121
	v_pk_add_f32 v[152:153], v[156:157], v[152:153]
	v_pk_add_f32 v[154:155], v[166:167], v[168:169]
	v_pk_add_f32 v[156:157], v[170:171], v[172:173]
	v_lshlrev_b32_e32 v141, 2, v141
	v_pk_add_f32 v[154:155], v[154:155], v[156:157]
	v_bitop3_b32 v141, v141, 64, v232 bitop3:0x6c
	v_pk_add_f32 v[152:153], v[152:153], v[154:155]
	s_waitcnt vmcnt(0)
	v_pk_fma_f32 v[114:115], v[186:187], s[0:1], v[114:115] op_sel_hi:[1,0,1]
	v_mov_b32_e32 v142, v148
	v_pk_fma_f32 v[116:117], v[188:189], s[0:1], v[116:117] op_sel_hi:[1,0,1]
	v_lshlrev_b32_e32 v142, 2, v142
	v_mul_f32_e32 v143, v114, v114
	v_mul_f32_e32 v145, v115, v115
	v_mul_f32_e32 v147, v116, v116
	v_mul_f32_e32 v175, v117, v117
	v_bitop3_b32 v149, v142, 64, v232 bitop3:0x6c
	v_mov_b32_e32 v142, v114
	v_mov_b32_e32 v144, v115
	v_mov_b32_e32 v146, v116
	v_mov_b32_e32 v174, v117
	v_pk_add_f32 v[142:143], v[142:143], v[144:145]
	v_pk_add_f32 v[144:145], v[146:147], v[174:175]
	s_movk_i32 s0, 0x80
	v_pk_add_f32 v[142:143], v[142:143], v[144:145]
	s_nop 0
	v_pk_add_f32 v[142:143], v[152:153], v[142:143]
	ds_bpermute_b32 v144, v141, v142
	ds_bpermute_b32 v145, v149, v143
	v_mov_b32_e32 v141, v148
	s_waitcnt lgkmcnt(0)
	v_pk_add_f32 v[142:143], v[142:143], v[144:145]
	v_lshlrev_b32_e32 v141, 2, v141
	v_bitop3_b32 v141, v141, s0, v232 bitop3:0x6c
	ds_bpermute_b32 v144, v141, v142
	v_mov_b32_e32 v141, v148
	s_nop 0
	v_lshlrev_b32_e32 v141, 2, v141
	v_bitop3_b32 v141, v141, s0, v232 bitop3:0x6c
	ds_bpermute_b32 v145, v141, v143
	s_and_saveexec_b64 s[0:1], vcc
	s_mov_b32 s40, 0xfff00000
	s_mov_b32 s41, -1
	s_cbranch_execz .LBB0_1091
	s_lshl_b32 s8, s6, 2
	s_add_i32 s8, s8, 0
	v_lshl_add_u32 v141, v0, 3, s8
	s_waitcnt lgkmcnt(0)
	v_pk_add_f32 v[142:143], v[142:143], v[144:145]
	ds_write_b64 v141, v[142:143]
.LBB0_1091:
	s_or_b64 exec, exec, s[0:1]
	v_or_b32_e32 v149, 16, v0
	v_add_u32_e32 v142, s7, v149
	v_ashrrev_i32_e32 v143, 31, v142
	s_waitcnt lgkmcnt(0)
	v_lshlrev_b64 v[144:145], 13, v[142:143]
	v_lshl_add_u64 v[144:145], s[28:29], 0, v[144:145]
	v_lshl_add_u64 v[152:153], v[136:137], 2, v[144:145]
	global_load_dwordx4 v[176:179], v[152:153], off
	global_load_dwordx4 v[180:183], v[152:153], off offset:64
	global_load_dwordx4 v[184:187], v[152:153], off offset:512
	global_load_dwordx4 v[188:191], v[152:153], off offset:576
	s_mov_b32 s0, 0x3fb504f3
	v_mov_b32_e32 v141, v148
	s_waitcnt vmcnt(3)
	v_pk_fma_f32 v[112:113], v[178:179], s[0:1], v[112:113] op_sel_hi:[1,0,1]
	v_pk_fma_f32 v[110:111], v[176:177], s[0:1], v[110:111] op_sel_hi:[1,0,1]

	v_add_f32_e32 v154, v110, v111
	v_add_f32_e32 v156, v112, v113
	v_mul_f32_e32 v159, v110, v110
	v_mul_f32_e32 v161, v111, v111
	v_mul_f32_e32 v163, v112, v112
	v_mul_f32_e32 v165, v113, v113
	s_waitcnt vmcnt(2)
	v_pk_fma_f32 v[108:109], v[182:183], s[0:1], v[108:109] op_sel_hi:[1,0,1]
	v_pk_fma_f32 v[106:107], v[180:181], s[0:1], v[106:107] op_sel_hi:[1,0,1]
	v_mul_f32_e32 v144, v108, v108
	v_pk_fma_f32 v[166:167], v[108:109], v[108:109], v[144:145] op_sel_hi:[1,1,0]

	v_mul_f32_e32 v155, v106, v106
	v_mul_f32_e32 v157, v107, v107
	v_mov_b32_e32 v158, v106
	v_mov_b32_e32 v160, v107
	v_mov_b32_e32 v162, v108
	v_mov_b32_e32 v164, v109
	v_pk_add_f32 v[158:159], v[158:159], v[160:161]
	v_pk_add_f32 v[160:161], v[162:163], v[164:165]
	v_pk_add_f32 v[154:155], v[154:155], v[156:157]
	v_mov_b32_e32 v166, v1
	v_pk_add_f32 v[158:159], v[158:159], v[160:161]
	v_pk_add_f32 v[154:155], v[154:155], v[166:167]
	s_waitcnt vmcnt(1)
	v_pk_fma_f32 v[104:105], v[186:187], s[0:1], v[104:105] op_sel_hi:[1,0,1]
	v_pk_fma_f32 v[102:103], v[184:185], s[0:1], v[102:103] op_sel_hi:[1,0,1]

	v_mul_f32_e32 v169, v102, v102
	v_mul_f32_e32 v171, v103, v103
	v_mul_f32_e32 v173, v104, v104
	v_mul_f32_e32 v175, v105, v105
	v_mov_b32_e32 v168, v102
	v_mov_b32_e32 v170, v103
	v_mov_b32_e32 v172, v104
	v_mov_b32_e32 v174, v105
	v_pk_add_f32 v[154:155], v[158:159], v[154:155]
	v_pk_add_f32 v[156:157], v[168:169], v[170:171]
	v_pk_add_f32 v[158:159], v[172:173], v[174:175]
	v_lshlrev_b32_e32 v141, 2, v141
	v_pk_add_f32 v[156:157], v[156:157], v[158:159]
	v_bitop3_b32 v141, v141, 64, v232 bitop3:0x6c
	v_pk_add_f32 v[154:155], v[154:155], v[156:157]
	s_waitcnt vmcnt(0)
	v_pk_fma_f32 v[98:99], v[188:189], s[0:1], v[98:99] op_sel_hi:[1,0,1]
	v_mov_b32_e32 v144, v148
	v_pk_fma_f32 v[100:101], v[190:191], s[0:1], v[100:101] op_sel_hi:[1,0,1]
	v_lshlrev_b32_e32 v144, 2, v144
	v_mul_f32_e32 v145, v98, v98
	v_mul_f32_e32 v147, v99, v99
	v_mul_f32_e32 v153, v100, v100
	v_mul_f32_e32 v177, v101, v101
	v_bitop3_b32 v178, v144, 64, v232 bitop3:0x6c
	v_mov_b32_e32 v144, v98
	v_mov_b32_e32 v146, v99
	v_mov_b32_e32 v152, v100
	v_mov_b32_e32 v176, v101
	v_pk_add_f32 v[144:145], v[144:145], v[146:147]
	v_pk_add_f32 v[146:147], v[152:153], v[176:177]
	s_movk_i32 s0, 0x80
	v_pk_add_f32 v[144:145], v[144:145], v[146:147]
	s_nop 0
	v_pk_add_f32 v[144:145], v[154:155], v[144:145]
	ds_bpermute_b32 v146, v141, v144
	ds_bpermute_b32 v147, v178, v145
	v_mov_b32_e32 v141, v148
	s_waitcnt lgkmcnt(0)
	v_pk_add_f32 v[144:145], v[144:145], v[146:147]
	v_lshlrev_b32_e32 v141, 2, v141
	v_bitop3_b32 v141, v141, s0, v232 bitop3:0x6c
	ds_bpermute_b32 v146, v141, v144
	v_mov_b32_e32 v141, v148
	s_nop 0
	v_lshlrev_b32_e32 v141, 2, v141
	v_bitop3_b32 v141, v141, s0, v232 bitop3:0x6c
	ds_bpermute_b32 v147, v141, v145
	s_and_saveexec_b64 s[0:1], vcc
	s_cbranch_execz .LBB0_1093
	s_lshl_b32 s8, s6, 2
	s_add_i32 s8, s8, 0
	v_lshl_add_u32 v141, v149, 3, s8
	s_waitcnt lgkmcnt(0)
	v_pk_add_f32 v[144:145], v[144:145], v[146:147]
	ds_write_b64 v141, v[144:145]
.LBB0_1093:
	s_or_b64 exec, exec, s[0:1]
	v_or_b32_e32 v202, 32, v0
	v_add_u32_e32 v144, s7, v202
	v_ashrrev_i32_e32 v145, 31, v144
	s_waitcnt lgkmcnt(0)
	v_lshlrev_b64 v[146:147], 13, v[144:145]
	v_lshl_add_u64 v[146:147], s[28:29], 0, v[146:147]
	v_lshl_add_u64 v[146:147], v[136:137], 2, v[146:147]
	global_load_dwordx4 v[182:185], v[146:147], off
	global_load_dwordx4 v[186:189], v[146:147], off offset:64
	global_load_dwordx4 v[190:193], v[146:147], off offset:512
	global_load_dwordx4 v[194:197], v[146:147], off offset:576
	s_mov_b32 s0, 0x3fb504f3
	v_mov_b32_e32 v141, v148
	s_waitcnt vmcnt(3)
	v_pk_fma_f32 v[96:97], v[184:185], s[0:1], v[96:97] op_sel_hi:[1,0,1]
	v_pk_fma_f32 v[94:95], v[182:183], s[0:1], v[94:95] op_sel_hi:[1,0,1]

	v_add_f32_e32 v156, v94, v95
	v_add_f32_e32 v158, v96, v97
	v_mul_f32_e32 v161, v94, v94
	v_mul_f32_e32 v163, v95, v95
	v_mul_f32_e32 v165, v96, v96
	v_mul_f32_e32 v167, v97, v97
	s_waitcnt vmcnt(2)
	v_pk_fma_f32 v[92:93], v[188:189], s[0:1], v[92:93] op_sel_hi:[1,0,1]
	v_pk_fma_f32 v[90:91], v[186:187], s[0:1], v[90:91] op_sel_hi:[1,0,1]
	v_mul_f32_e32 v152, v92, v92
	v_pk_fma_f32 v[168:169], v[92:93], v[92:93], v[152:153] op_sel_hi:[1,1,0]

	v_mul_f32_e32 v157, v90, v90
	v_mul_f32_e32 v159, v91, v91
	v_mov_b32_e32 v160, v90
	v_mov_b32_e32 v162, v91
	v_mov_b32_e32 v164, v92
	v_mov_b32_e32 v166, v93
	v_pk_add_f32 v[160:161], v[160:161], v[162:163]
	v_pk_add_f32 v[162:163], v[164:165], v[166:167]
	v_pk_add_f32 v[156:157], v[156:157], v[158:159]
	v_mov_b32_e32 v168, v1
	v_pk_add_f32 v[160:161], v[160:161], v[162:163]
	v_pk_add_f32 v[156:157], v[156:157], v[168:169]
	s_waitcnt vmcnt(1)
	v_pk_fma_f32 v[88:89], v[192:193], s[0:1], v[88:89] op_sel_hi:[1,0,1]
	v_pk_fma_f32 v[86:87], v[190:191], s[0:1], v[86:87] op_sel_hi:[1,0,1]

	v_mov_b32_e32 v146, v148
	v_mul_f32_e32 v171, v86, v86
	v_mul_f32_e32 v173, v87, v87
	v_mul_f32_e32 v175, v88, v88
	v_mul_f32_e32 v177, v89, v89
	v_lshlrev_b32_e32 v146, 2, v146
	v_mov_b32_e32 v170, v86
	v_mov_b32_e32 v172, v87
	v_mov_b32_e32 v174, v88
	v_mov_b32_e32 v176, v89
	v_bitop3_b32 v180, v146, 64, v232 bitop3:0x6c
	v_pk_add_f32 v[156:157], v[160:161], v[156:157]
	v_pk_add_f32 v[158:159], v[170:171], v[172:173]
	v_pk_add_f32 v[160:161], v[174:175], v[176:177]
	v_lshlrev_b32_e32 v141, 2, v141
	v_pk_add_f32 v[158:159], v[158:159], v[160:161]
	v_bitop3_b32 v141, v141, 64, v232 bitop3:0x6c
	v_pk_add_f32 v[156:157], v[156:157], v[158:159]
	s_waitcnt vmcnt(0)
	v_pk_fma_f32 v[84:85], v[196:197], s[0:1], v[84:85] op_sel_hi:[1,0,1]
	v_pk_fma_f32 v[82:83], v[194:195], s[0:1], v[82:83] op_sel_hi:[1,0,1]
	v_mul_f32_e32 v155, v84, v84
	v_mul_f32_e32 v147, v82, v82
	v_mul_f32_e32 v153, v83, v83
	v_mul_f32_e32 v179, v85, v85
	v_mov_b32_e32 v146, v82
	v_mov_b32_e32 v152, v83
	v_mov_b32_e32 v154, v84
	v_mov_b32_e32 v178, v85
	v_pk_add_f32 v[146:147], v[146:147], v[152:153]
	v_pk_add_f32 v[152:153], v[154:155], v[178:179]
	s_movk_i32 s0, 0x80
	v_pk_add_f32 v[146:147], v[146:147], v[152:153]
	s_nop 0
	v_pk_add_f32 v[146:147], v[156:157], v[146:147]
	ds_bpermute_b32 v152, v141, v146
	ds_bpermute_b32 v153, v180, v147
	v_mov_b32_e32 v141, v148
	s_waitcnt lgkmcnt(0)
	v_pk_add_f32 v[146:147], v[146:147], v[152:153]
	v_lshlrev_b32_e32 v141, 2, v141
	v_bitop3_b32 v141, v141, s0, v232 bitop3:0x6c
	ds_bpermute_b32 v156, v141, v146
	v_mov_b32_e32 v141, v148
	s_nop 0
	v_lshlrev_b32_e32 v141, 2, v141
	v_bitop3_b32 v141, v141, s0, v232 bitop3:0x6c
	ds_bpermute_b32 v157, v141, v147
	s_and_saveexec_b64 s[0:1], vcc
	s_cbranch_execz .LBB0_1095
	s_lshl_b32 s8, s6, 2
	s_add_i32 s8, s8, 0
	v_lshl_add_u32 v141, v202, 3, s8
	s_waitcnt lgkmcnt(0)
	v_pk_add_f32 v[146:147], v[146:147], v[156:157]
	ds_write_b64 v141, v[146:147]
.LBB0_1095:
	s_or_b64 exec, exec, s[0:1]
	v_or_b32_e32 v203, 48, v0
	v_add_u32_e32 v146, s7, v203
	v_ashrrev_i32_e32 v147, 31, v146
	v_lshlrev_b64 v[152:153], 13, v[146:147]
	v_lshl_add_u64 v[152:153], s[28:29], 0, v[152:153]
	s_waitcnt lgkmcnt(0)
	v_lshl_add_u64 v[156:157], v[136:137], 2, v[152:153]
	global_load_dwordx4 v[180:183], v[156:157], off
	global_load_dwordx4 v[184:187], v[156:157], off offset:64
	global_load_dwordx4 v[188:191], v[156:157], off offset:512
	global_load_dwordx4 v[192:195], v[156:157], off offset:576
	s_mov_b32 s0, 0x3fb504f3
	v_mov_b32_e32 v141, v148
	s_waitcnt vmcnt(3)
	v_pk_fma_f32 v[80:81], v[182:183], s[0:1], v[80:81] op_sel_hi:[1,0,1]
	v_pk_fma_f32 v[78:79], v[180:181], s[0:1], v[78:79] op_sel_hi:[1,0,1]

	v_add_f32_e32 v158, v78, v79
	v_add_f32_e32 v160, v80, v81
	v_mul_f32_e32 v163, v78, v78
	v_mul_f32_e32 v165, v79, v79
	v_mul_f32_e32 v167, v80, v80
	v_mul_f32_e32 v169, v81, v81
	s_waitcnt vmcnt(2)
	v_pk_fma_f32 v[76:77], v[186:187], s[0:1], v[76:77] op_sel_hi:[1,0,1]
	v_pk_fma_f32 v[74:75], v[184:185], s[0:1], v[74:75] op_sel_hi:[1,0,1]
	v_mul_f32_e32 v152, v76, v76
	v_pk_fma_f32 v[170:171], v[76:77], v[76:77], v[152:153] op_sel_hi:[1,1,0]

	v_mul_f32_e32 v159, v74, v74
	v_mul_f32_e32 v161, v75, v75
	v_mov_b32_e32 v162, v74
	v_mov_b32_e32 v164, v75
	v_mov_b32_e32 v166, v76
	v_mov_b32_e32 v168, v77
	v_pk_add_f32 v[162:163], v[162:163], v[164:165]
	v_pk_add_f32 v[164:165], v[166:167], v[168:169]
	v_pk_add_f32 v[158:159], v[158:159], v[160:161]
	v_mov_b32_e32 v170, v1
	v_pk_add_f32 v[162:163], v[162:163], v[164:165]
	v_pk_add_f32 v[158:159], v[158:159], v[170:171]
	s_waitcnt vmcnt(1)
	v_pk_fma_f32 v[72:73], v[190:191], s[0:1], v[72:73] op_sel_hi:[1,0,1]
	v_pk_fma_f32 v[70:71], v[188:189], s[0:1], v[70:71] op_sel_hi:[1,0,1]

	v_mul_f32_e32 v173, v70, v70
	v_mul_f32_e32 v175, v71, v71
	v_mul_f32_e32 v177, v72, v72
	v_mul_f32_e32 v179, v73, v73
	v_mov_b32_e32 v172, v70
	v_mov_b32_e32 v174, v71
	v_mov_b32_e32 v176, v72
	v_mov_b32_e32 v178, v73
	v_pk_add_f32 v[158:159], v[162:163], v[158:159]
	v_pk_add_f32 v[160:161], v[172:173], v[174:175]
	v_pk_add_f32 v[162:163], v[176:177], v[178:179]
	v_lshlrev_b32_e32 v141, 2, v141
	v_pk_add_f32 v[160:161], v[160:161], v[162:163]
	v_bitop3_b32 v141, v141, 64, v232 bitop3:0x6c
	v_pk_add_f32 v[158:159], v[158:159], v[160:161]
	s_waitcnt vmcnt(0)
	v_pk_fma_f32 v[66:67], v[192:193], s[0:1], v[66:67] op_sel_hi:[1,0,1]
	v_mov_b32_e32 v152, v148
	v_pk_fma_f32 v[68:69], v[194:195], s[0:1], v[68:69] op_sel_hi:[1,0,1]
	v_lshlrev_b32_e32 v152, 2, v152
	v_mul_f32_e32 v153, v66, v66
	v_mul_f32_e32 v155, v67, v67
	v_mul_f32_e32 v157, v68, v68
	v_mul_f32_e32 v181, v69, v69
	v_bitop3_b32 v182, v152, 64, v232 bitop3:0x6c
	v_mov_b32_e32 v152, v66
	v_mov_b32_e32 v154, v67
	v_mov_b32_e32 v156, v68
	v_mov_b32_e32 v180, v69
	v_pk_add_f32 v[152:153], v[152:153], v[154:155]
	v_pk_add_f32 v[154:155], v[156:157], v[180:181]
	s_movk_i32 s0, 0x80
	v_pk_add_f32 v[152:153], v[152:153], v[154:155]
	s_nop 0
	v_pk_add_f32 v[152:153], v[158:159], v[152:153]
	ds_bpermute_b32 v154, v141, v152
	ds_bpermute_b32 v155, v182, v153
	v_mov_b32_e32 v141, v148
	s_waitcnt lgkmcnt(0)
	v_pk_add_f32 v[156:157], v[152:153], v[154:155]
	v_lshlrev_b32_e32 v141, 2, v141
	v_bitop3_b32 v141, v141, s0, v232 bitop3:0x6c
	ds_bpermute_b32 v158, v141, v156
	v_mov_b32_e32 v141, v148
	s_nop 0
	v_lshlrev_b32_e32 v141, 2, v141
	v_bitop3_b32 v141, v141, s0, v232 bitop3:0x6c
	ds_bpermute_b32 v159, v141, v157
	s_and_saveexec_b64 s[0:1], vcc
	s_cbranch_execz .LBB0_1097
	s_lshl_b32 s8, s6, 2
	s_add_i32 s8, s8, 0
	v_lshl_add_u32 v141, v203, 3, s8
	s_waitcnt lgkmcnt(0)
	v_pk_add_f32 v[152:153], v[156:157], v[158:159]
	ds_write_b64 v141, v[152:153]
.LBB0_1097:
	s_or_b64 exec, exec, s[0:1]
	v_add_u32_e32 v204, 0x80, v0
	v_add_u32_e32 v156, s7, v204
	v_ashrrev_i32_e32 v157, 31, v156
	v_lshlrev_b64 v[152:153], 13, v[156:157]
	v_lshl_add_u64 v[152:153], s[28:29], 0, v[152:153]
	s_waitcnt lgkmcnt(0)
	v_lshl_add_u64 v[158:159], v[136:137], 2, v[152:153]
	global_load_dwordx4 v[182:185], v[158:159], off
	global_load_dwordx4 v[186:189], v[158:159], off offset:64
	global_load_dwordx4 v[190:193], v[158:159], off offset:512
	global_load_dwordx4 v[194:197], v[158:159], off offset:576
	s_mov_b32 s0, 0x3fb504f3
	v_mov_b32_e32 v141, v148
	s_waitcnt vmcnt(3)
	v_pk_fma_f32 v[64:65], v[184:185], s[0:1], v[64:65] op_sel_hi:[1,0,1]
	v_pk_fma_f32 v[62:63], v[182:183], s[0:1], v[62:63] op_sel_hi:[1,0,1]

	v_add_f32_e32 v160, v62, v63
	v_add_f32_e32 v162, v64, v65
	v_mul_f32_e32 v165, v62, v62
	v_mul_f32_e32 v167, v63, v63
	v_mul_f32_e32 v169, v64, v64
	v_mul_f32_e32 v171, v65, v65
	s_waitcnt vmcnt(2)
	v_pk_fma_f32 v[60:61], v[188:189], s[0:1], v[60:61] op_sel_hi:[1,0,1]
	v_pk_fma_f32 v[58:59], v[186:187], s[0:1], v[58:59] op_sel_hi:[1,0,1]
	v_mul_f32_e32 v152, v60, v60
	v_pk_fma_f32 v[172:173], v[60:61], v[60:61], v[152:153] op_sel_hi:[1,1,0]

	v_mul_f32_e32 v161, v58, v58
	v_mul_f32_e32 v163, v59, v59
	v_mov_b32_e32 v164, v58
	v_mov_b32_e32 v166, v59
	v_mov_b32_e32 v168, v60
	v_mov_b32_e32 v170, v61
	v_pk_add_f32 v[164:165], v[164:165], v[166:167]
	v_pk_add_f32 v[166:167], v[168:169], v[170:171]
	v_pk_add_f32 v[160:161], v[160:161], v[162:163]
	v_mov_b32_e32 v172, v1
	v_pk_add_f32 v[164:165], v[164:165], v[166:167]
	v_pk_add_f32 v[160:161], v[160:161], v[172:173]
	s_waitcnt vmcnt(1)
	v_pk_fma_f32 v[56:57], v[192:193], s[0:1], v[56:57] op_sel_hi:[1,0,1]
	v_pk_fma_f32 v[54:55], v[190:191], s[0:1], v[54:55] op_sel_hi:[1,0,1]

	v_mul_f32_e32 v175, v54, v54
	v_mul_f32_e32 v177, v55, v55
	v_mul_f32_e32 v179, v56, v56
	v_mul_f32_e32 v181, v57, v57
	v_mov_b32_e32 v174, v54
	v_mov_b32_e32 v176, v55
	v_mov_b32_e32 v178, v56
	v_mov_b32_e32 v180, v57
	v_pk_add_f32 v[160:161], v[164:165], v[160:161]
	v_pk_add_f32 v[162:163], v[174:175], v[176:177]
	v_pk_add_f32 v[164:165], v[178:179], v[180:181]
	v_lshlrev_b32_e32 v141, 2, v141
	v_pk_add_f32 v[162:163], v[162:163], v[164:165]
	v_bitop3_b32 v141, v141, 64, v232 bitop3:0x6c
	v_pk_add_f32 v[160:161], v[160:161], v[162:163]
	s_waitcnt vmcnt(0)
	v_pk_fma_f32 v[50:51], v[194:195], s[0:1], v[50:51] op_sel_hi:[1,0,1]
	v_mov_b32_e32 v152, v148
	v_pk_fma_f32 v[52:53], v[196:197], s[0:1], v[52:53] op_sel_hi:[1,0,1]
	v_lshlrev_b32_e32 v152, 2, v152
	v_mul_f32_e32 v153, v50, v50
	v_mul_f32_e32 v155, v51, v51
	v_mul_f32_e32 v159, v52, v52
	v_mul_f32_e32 v183, v53, v53
	v_bitop3_b32 v184, v152, 64, v232 bitop3:0x6c
	v_mov_b32_e32 v152, v50
	v_mov_b32_e32 v154, v51
	v_mov_b32_e32 v158, v52
	v_mov_b32_e32 v182, v53
	v_pk_add_f32 v[152:153], v[152:153], v[154:155]
	v_pk_add_f32 v[154:155], v[158:159], v[182:183]
	s_movk_i32 s0, 0x80
	v_pk_add_f32 v[152:153], v[152:153], v[154:155]
	s_nop 0
	v_pk_add_f32 v[152:153], v[160:161], v[152:153]
	ds_bpermute_b32 v154, v141, v152
	ds_bpermute_b32 v155, v184, v153
	v_mov_b32_e32 v141, v148
	s_waitcnt lgkmcnt(0)
	v_pk_add_f32 v[158:159], v[152:153], v[154:155]
	v_lshlrev_b32_e32 v141, 2, v141
	v_bitop3_b32 v141, v141, s0, v232 bitop3:0x6c
	ds_bpermute_b32 v160, v141, v158
	v_mov_b32_e32 v141, v148
	s_nop 0
	v_lshlrev_b32_e32 v141, 2, v141
	v_bitop3_b32 v141, v141, s0, v232 bitop3:0x6c
	ds_bpermute_b32 v161, v141, v159
	s_and_saveexec_b64 s[0:1], vcc
	s_cbranch_execz .LBB0_1099
	s_lshl_b32 s8, s6, 2
	s_add_i32 s8, s8, 0
	v_lshl_add_u32 v141, v204, 3, s8
	s_waitcnt lgkmcnt(0)
	v_pk_add_f32 v[152:153], v[158:159], v[160:161]
	ds_write_b64 v141, v[152:153]

.LBB0_1101:
	s_or_b64 exec, exec, s[0:1]
	v_add_u32_e32 v206, 0xa0, v0
	v_add_u32_e32 v164, s7, v206
	v_ashrrev_i32_e32 v165, 31, v164
	v_lshlrev_b64 v[34:35], 13, v[164:165]
	v_lshl_add_u64 v[34:35], s[28:29], 0, v[34:35]
	v_lshl_add_u64 v[152:153], v[136:137], 2, v[34:35]
	s_waitcnt lgkmcnt(0)
	global_load_dwordx4 v[190:193], v[152:153], off
	global_load_dwordx4 v[194:197], v[152:153], off offset:64
	global_load_dwordx4 v[198:201], v[152:153], off offset:512
	global_load_dwordx4 v[216:219], v[152:153], off offset:576
	s_mov_b32 s0, 0x3fb504f3
	s_waitcnt vmcnt(3)
	v_pk_fma_f32 v[180:181], v[192:193], s[0:1], v[32:33] op_sel_hi:[1,0,1]
	v_pk_fma_f32 v[178:179], v[190:191], s[0:1], v[30:31] op_sel_hi:[1,0,1]

	v_add_f32_e32 v34, v178, v179
	v_add_f32_e32 v36, v180, v181
	v_mul_f32_e32 v155, v178, v178
	v_mul_f32_e32 v183, v179, v179
	v_mul_f32_e32 v185, v180, v180
	v_mul_f32_e32 v187, v181, v181
	s_waitcnt vmcnt(2)
	v_pk_fma_f32 v[176:177], v[196:197], s[0:1], v[28:29] op_sel_hi:[1,0,1]
	v_pk_fma_f32 v[174:175], v[194:195], s[0:1], v[26:27] op_sel_hi:[1,0,1]
	v_mul_f32_e32 v26, v176, v176
	v_pk_fma_f32 v[30:31], v[176:177], v[176:177], v[26:27] op_sel_hi:[1,1,0]

	v_mul_f32_e32 v35, v174, v174
	v_mul_f32_e32 v37, v175, v175
	v_mov_b32_e32 v154, v174
	v_mov_b32_e32 v182, v175
	v_mov_b32_e32 v184, v176
	v_mov_b32_e32 v186, v177
	v_pk_add_f32 v[34:35], v[34:35], v[36:37]
	v_mov_b32_e32 v30, v1
	v_pk_add_f32 v[30:31], v[34:35], v[30:31]
	s_waitcnt vmcnt(1)
	v_pk_fma_f32 v[172:173], v[200:201], s[0:1], v[24:25] op_sel_hi:[1,0,1]
	v_pk_fma_f32 v[170:171], v[198:199], s[0:1], v[22:23] op_sel_hi:[1,0,1]

	v_mul_f32_e32 v27, v170, v170
	v_mul_f32_e32 v29, v171, v171
	v_mul_f32_e32 v33, v172, v172
	v_mul_f32_e32 v189, v173, v173
	v_pk_add_f32 v[152:153], v[154:155], v[182:183]
	v_pk_add_f32 v[154:155], v[184:185], v[186:187]
	v_mov_b32_e32 v26, v170
	v_mov_b32_e32 v28, v171
	v_mov_b32_e32 v32, v172
	v_mov_b32_e32 v188, v173
	v_pk_add_f32 v[152:153], v[152:153], v[154:155]
	v_pk_add_f32 v[26:27], v[26:27], v[28:29]
	v_pk_add_f32 v[28:29], v[32:33], v[188:189]
	v_pk_add_f32 v[30:31], v[152:153], v[30:31]
	v_pk_add_f32 v[26:27], v[26:27], v[28:29]
	s_waitcnt vmcnt(0)
	v_pk_fma_f32 v[168:169], v[216:217], s[0:1], v[18:19] op_sel_hi:[1,0,1]
	v_mov_b32_e32 v18, v148
	v_pk_fma_f32 v[166:167], v[218:219], s[0:1], v[20:21] op_sel_hi:[1,0,1]
	v_lshlrev_b32_e32 v18, 2, v18
	v_bitop3_b32 v141, v18, 64, v232 bitop3:0x6c
	v_mov_b32_e32 v18, v148
	v_mul_f32_e32 v19, v168, v168
	v_lshlrev_b32_e32 v18, 2, v18
	v_mul_f32_e32 v21, v169, v169
	v_mul_f32_e32 v23, v166, v166
	v_mul_f32_e32 v25, v167, v167
	v_bitop3_b32 v190, v18, 64, v232 bitop3:0x6c
	v_mov_b32_e32 v18, v168
	v_mov_b32_e32 v20, v169
	v_mov_b32_e32 v22, v166
	v_mov_b32_e32 v24, v167
	v_pk_add_f32 v[18:19], v[18:19], v[20:21]
	v_pk_add_f32 v[20:21], v[22:23], v[24:25]
	v_pk_add_f32 v[26:27], v[30:31], v[26:27]
	v_pk_add_f32 v[18:19], v[18:19], v[20:21]
	s_movk_i32 s0, 0x80
	v_pk_add_f32 v[18:19], v[26:27], v[18:19]
	ds_bpermute_b32 v20, v141, v18
	ds_bpermute_b32 v21, v190, v19
	s_waitcnt lgkmcnt(0)
	v_pk_add_f32 v[18:19], v[18:19], v[20:21]
	v_mov_b32_e32 v20, v148
	v_mov_b32_e32 v21, v148
	s_nop 0
	v_lshlrev_b32_e32 v20, 2, v20
	v_lshlrev_b32_e32 v21, 2, v21
	v_bitop3_b32 v20, v20, s0, v232 bitop3:0x6c
	v_bitop3_b32 v21, v21, s0, v232 bitop3:0x6c
	ds_bpermute_b32 v20, v20, v18
	ds_bpermute_b32 v21, v21, v19
	s_and_saveexec_b64 s[0:1], vcc
	s_cbranch_execz .LBB0_1103
	s_lshl_b32 s8, s6, 2
	s_add_i32 s8, s8, 0
	v_lshl_add_u32 v22, v206, 3, s8
	s_waitcnt lgkmcnt(0)
	v_pk_add_f32 v[18:19], v[18:19], v[20:21]
	ds_write_b64 v22, v[18:19]
.LBB0_1103:
	s_or_b64 exec, exec, s[0:1]
	v_add_u32_e32 v207, 0xb0, v0
	v_add_u32_e32 v182, s7, v207
	v_ashrrev_i32_e32 v183, 31, v182
	v_lshlrev_b64 v[18:19], 13, v[182:183]
	v_lshl_add_u64 v[18:19], s[28:29], 0, v[18:19]
	v_lshl_add_u64 v[22:23], v[136:137], 2, v[18:19]
	s_waitcnt lgkmcnt(0)
	global_load_dwordx4 v[152:155], v[22:23], off
	global_load_dwordx4 v[216:219], v[22:23], off offset:64
	global_load_dwordx4 v[220:223], v[22:23], off offset:512
	global_load_dwordx4 v[224:227], v[22:23], off offset:576
	s_mov_b32 s0, 0x3fb504f3
	s_movk_i32 s70, 0x80
	s_waitcnt vmcnt(3)
	v_pk_fma_f32 v[198:199], v[154:155], s[0:1], v[16:17] op_sel_hi:[1,0,1]
	v_pk_fma_f32 v[196:197], v[152:153], s[0:1], v[14:15] op_sel_hi:[1,0,1]

	v_add_f32_e32 v18, v196, v197
	v_add_f32_e32 v20, v198, v199
	v_mul_f32_e32 v25, v196, v196
	v_mul_f32_e32 v27, v197, v197
	v_mul_f32_e32 v29, v198, v198
	v_mul_f32_e32 v31, v199, v199
	s_waitcnt vmcnt(2)
	v_pk_fma_f32 v[194:195], v[218:219], s[0:1], v[12:13] op_sel_hi:[1,0,1]
	v_pk_fma_f32 v[192:193], v[216:217], s[0:1], v[10:11] op_sel_hi:[1,0,1]
	v_mul_f32_e32 v10, v194, v194
	v_pk_fma_f32 v[14:15], v[194:195], v[194:195], v[10:11] op_sel_hi:[1,1,0]

	v_mul_f32_e32 v19, v192, v192
	v_mul_f32_e32 v21, v193, v193
	v_mov_b32_e32 v24, v192
	v_mov_b32_e32 v26, v193
	v_mov_b32_e32 v28, v194
	v_mov_b32_e32 v30, v195
	v_pk_add_f32 v[18:19], v[18:19], v[20:21]
	v_mov_b32_e32 v14, v1
	v_pk_add_f32 v[14:15], v[18:19], v[14:15]
	s_waitcnt vmcnt(1)
	v_pk_fma_f32 v[190:191], v[222:223], s[0:1], v[8:9] op_sel_hi:[1,0,1]
	v_pk_fma_f32 v[188:189], v[220:221], s[0:1], v[6:7] op_sel_hi:[1,0,1]

	v_mul_f32_e32 v11, v188, v188
	v_mul_f32_e32 v13, v189, v189
	v_mul_f32_e32 v17, v190, v190
	v_mul_f32_e32 v33, v191, v191
	v_pk_add_f32 v[22:23], v[24:25], v[26:27]
	v_pk_add_f32 v[24:25], v[28:29], v[30:31]
	v_mov_b32_e32 v10, v188
	v_mov_b32_e32 v12, v189
	v_mov_b32_e32 v16, v190
	v_mov_b32_e32 v32, v191
	v_pk_add_f32 v[22:23], v[22:23], v[24:25]
	v_pk_add_f32 v[10:11], v[10:11], v[12:13]
	v_pk_add_f32 v[12:13], v[16:17], v[32:33]
	v_pk_add_f32 v[14:15], v[22:23], v[14:15]
	v_pk_add_f32 v[10:11], v[10:11], v[12:13]
	s_waitcnt vmcnt(0)
	v_pk_fma_f32 v[186:187], v[224:225], s[0:1], v[2:3] op_sel_hi:[1,0,1]
	v_mov_b32_e32 v2, v148
	v_pk_fma_f32 v[184:185], v[226:227], s[0:1], v[4:5] op_sel_hi:[1,0,1]
	v_lshlrev_b32_e32 v2, 2, v2
	v_bitop3_b32 v34, v2, 64, v232 bitop3:0x6c
	v_mov_b32_e32 v2, v148
	v_mul_f32_e32 v3, v186, v186
	v_lshlrev_b32_e32 v2, 2, v2
	v_mul_f32_e32 v5, v187, v187
	v_mul_f32_e32 v7, v184, v184
	v_mul_f32_e32 v9, v185, v185
	v_bitop3_b32 v35, v2, 64, v232 bitop3:0x6c
	v_mov_b32_e32 v2, v186
	v_mov_b32_e32 v4, v187
	v_mov_b32_e32 v6, v184
	v_mov_b32_e32 v8, v185
	v_pk_add_f32 v[2:3], v[2:3], v[4:5]
	v_pk_add_f32 v[4:5], v[6:7], v[8:9]
	v_pk_add_f32 v[10:11], v[14:15], v[10:11]
	v_pk_add_f32 v[2:3], v[2:3], v[4:5]
	s_movk_i32 s0, 0x80
	v_pk_add_f32 v[2:3], v[10:11], v[2:3]
	ds_bpermute_b32 v4, v34, v2
	ds_bpermute_b32 v5, v35, v3
	s_waitcnt lgkmcnt(0)
	v_pk_add_f32 v[2:3], v[2:3], v[4:5]
	v_mov_b32_e32 v4, v148
	v_mov_b32_e32 v5, v148
	s_nop 0
	v_lshlrev_b32_e32 v4, 2, v4
	v_lshlrev_b32_e32 v5, 2, v5
	v_bitop3_b32 v4, v4, s0, v232 bitop3:0x6c
	v_bitop3_b32 v5, v5, s0, v232 bitop3:0x6c
	ds_bpermute_b32 v4, v4, v2
	ds_bpermute_b32 v5, v5, v3
	s_and_saveexec_b64 s[0:1], vcc
	s_cbranch_execz .LBB0_1105
	s_lshl_b32 s6, s6, 2
	s_add_i32 s6, s6, 0
	v_lshl_add_u32 v6, v207, 3, s6
	s_waitcnt lgkmcnt(0)
	v_pk_add_f32 v[2:3], v[2:3], v[4:5]
	ds_write_b64 v6, v[2:3]
